# v28 + attention LDS-DMA issue blocks: dropped the m0 save/restore pair around each global_load_lds (m0 is dead there)
# speedup vs baseline: 1.0091x; 1.0091x over previous
; #define AT_WAITBAR(N) asm volatile("s_waitcnt vmcnt(%0) lgkmcnt(0)\n\ts_barrier" :: "n"(N) : "memory")
; template <int DQK, int DV, bool BAND>
; DI void attn_unit(const AttnArgs& a, LAS unsigned char* lds, int tid) {
;     ...
;     if (wid >= 4) __builtin_amdgcn_s_setprio(1);
;     f32x16 o[NDB], lacc, negm;
; #pragma unroll
;     for (int d = 0; d < NDB; ++d)
; #pragma unroll
;         for (int r = 0; r < 16; ++r) o[d][r] = 0.f;
; #pragma unroll
;     for (int r = 0; r < 16; ++r) { lacc[r] = 0.f; negm[r] = 0.f; }
;     float m_run = 0.f; bool first = true;
;     const bf16x8 ones = (bf16x8){(short)0x3F80, (short)0x3F80, (short)0x3F80, (short)0x3F80, (short)0x3F80, (short)0x3F80, (short)0x3F80, (short)0x3F80};
;     if (BAND) {
;         for (int t = t_lo; t < t_hi; ++t) AT_DMA(t, (t - t_lo) * 8192);
;         AT_WAITBAR(0);
;     } else {
;         AT_DMA(t_lo, 0);
;         if (t_lo + 1 < t_hi) AT_DMA(t_lo + 1, 16384);
;     }
; __global__ void __launch_bounds__(512, 2) mega_fwd(Params p) {
;     ...
;                             const int h = u & 3, rb = u >> 2; const int sq = (rb * 256) / S;
;                             const bf16_t* kvb = KVM + ((size_t)li * NMEMROWS + (size_t)(gseq0 + sq) * 256) * DM + h * 128;
;                             AttnArgs a; a.nomax = 0; a.q = QX + (size_t)rb * 256 * 512 + h * 128; a.qs = 512; a.k = kvb; a.ks = DM; a.k2 = nullptr; a.k2s = 0; a.v = kvb + 512; a.vs = DM;
;                             a.o = AO + (size_t)rb * 256 * 512 + h * 128; a.os = 512; a.lse = nullptr; a.lses = 0; a.kv_len = 256; a.q0 = 0;
;                             attn_unit<128, 128, false>(a, lds, tid);
.LBB0_127:
	s_lshl_b32 s26, s16, 1
	s_and_b32 s54, s26, 0x300
	s_lshl_b32 s26, s40, 8
	s_ashr_i32 s27, s26, 31
	s_abs_i32 s26, s26
	s_lshl_b64 s[42:43], s[40:41], 17
	s_mul_hi_u32 s34, s26, s91
	v_readlane_b32 s41, v254, 29
	s_mul_i32 s35, s34, s41
	s_sub_i32 s26, s26, s35
	s_add_i32 s35, s34, 1
	s_sub_i32 s40, s26, s41
	s_cmp_ge_u32 s26, s41
	s_cselect_b32 s34, s35, s34
	s_cselect_b32 s26, s40, s26
	s_add_i32 s35, s34, 1
	s_cmp_ge_u32 s26, s41
	s_cselect_b32 s26, s35, s34
	s_xor_b32 s26, s26, s27
	s_sub_i32 s26, s26, s27
	v_readlane_b32 s27, v254, 20
	s_add_i32 s26, s26, s27
	s_ashr_i32 s27, s26, 31
	s_lshl_b64 s[40:41], s[26:27], 19
	s_add_u32 s26, s12, s40
	s_addc_u32 s27, s13, s41
	s_add_u32 s44, s26, s24
	s_addc_u32 s45, s27, 0
	s_lshl_b32 s26, s19, 8
	s_add_i32 s26, s26, 0
	s_lshl_b32 s34, s19, 3
	s_add_i32 s55, s26, 0x18000
	s_ashr_i32 s35, s34, 31
	s_lshl_b32 s26, s19, 10
	s_lshl_b64 s[46:47], s[34:35], 1
	s_add_i32 s27, s26, 0
	s_add_i32 s56, s19, 8
	v_lshl_add_u64 v[0:1], s[44:45], 0, v[160:161]
	s_cmp_lt_i32 s19, 8
	v_lshl_add_u64 v[2:3], v[0:1], 0, s[46:47]
	s_mov_b32 m0, s27
	s_nop 0
	global_load_lds_dwordx4 v[2:3], off
	s_cselect_b32 s27, s56, s19
	s_lshl_b32 s48, s27, 3
	s_ashr_i32 s49, s48, 31
	s_lshl_b32 s27, s27, 10
	s_lshl_b64 s[48:49], s[48:49], 1
	s_add_i32 s35, s27, 0
	v_lshl_add_u64 v[0:1], v[0:1], 0, s[48:49]
	s_mov_b32 m0, s35
	s_nop 0
	global_load_lds_dwordx4 v[0:1], off
	s_lshl_b32 s35, s19, 4
	v_and_or_b32 v0, s35, 48, v183
	s_andn2_b32 s34, s34, 31
	s_ashr_i32 s35, s34, 31
	v_lshlrev_b32_e32 v0, 11, v0
	v_mov_b32_e32 v1, v195
	s_lshl_b64 s[50:51], s[34:35], 1
	v_lshl_add_u64 v[2:3], s[44:45], 0, v[0:1]
	v_lshl_add_u64 v[4:5], v[2:3], 0, s[50:51]
	v_mov_b32_e32 v167, v195
	s_add_i32 s57, 0, 0xc000
	v_lshl_add_u64 v[4:5], v[4:5], 0, v[166:167]
	s_mov_b64 s[70:71], 0x400
	s_add_i32 s34, s26, s57
	v_lshl_add_u64 v[4:5], v[4:5], 0, s[70:71]
	s_mov_b32 m0, s34
	s_nop 0
	global_load_lds_dwordx4 v[4:5], off
	s_lshl_b32 s34, s56, 3
	s_andn2_b32 s34, s34, 31
	s_ashr_i32 s35, s34, 31
	s_lshl_b64 s[52:53], s[34:35], 1
	v_lshl_add_u64 v[4:5], v[2:3], 0, s[52:53]
	v_lshl_add_u64 v[4:5], v[4:5], 0, v[166:167]
	v_lshl_add_u64 v[4:5], v[4:5], 0, s[70:71]
	s_lshl_b32 s34, s56, 10
	v_mov_b32_e32 v169, v195
	s_add_i32 s35, s34, s57
	s_mov_b32 m0, s35
	s_nop 0
	global_load_lds_dwordx4 v[4:5], off
	v_lshl_add_u64 v[4:5], s[44:45], 0, v[168:169]
	s_mov_b64 s[44:45], 0x20000
	v_lshl_add_u64 v[4:5], v[4:5], 0, s[44:45]
	v_readlane_b32 s45, v253, 36
	v_lshl_add_u64 v[6:7], v[4:5], 0, s[46:47]
	s_add_i32 s35, s26, s45
	s_mov_b32 m0, s35
	s_nop 0
	global_load_lds_dwordx4 v[6:7], off
	v_lshl_add_u64 v[4:5], v[4:5], 0, s[48:49]
	s_add_i32 s35, s27, s45
	s_mov_b32 m0, s35
	s_nop 0
	global_load_lds_dwordx4 v[4:5], off
	s_mov_b64 s[44:45], 0x20400
	v_lshl_add_u64 v[2:3], v[2:3], 0, s[44:45]
	v_lshl_add_u64 v[4:5], v[2:3], 0, s[50:51]
	s_add_i32 s35, 0, 0x10000
	v_lshl_add_u64 v[4:5], v[4:5], 0, v[166:167]
	s_add_i32 s44, s26, s35
	s_mov_b32 m0, s44
	s_nop 0
	global_load_lds_dwordx4 v[4:5], off
	v_lshl_add_u64 v[2:3], v[2:3], 0, s[52:53]
	s_add_i32 s35, s34, s35
	v_lshl_add_u64 v[2:3], v[2:3], 0, v[166:167]
	s_mov_b32 m0, s35
	s_nop 0
	global_load_lds_dwordx4 v[2:3], off
	s_or_b32 s35, s40, s54
	s_add_u32 s44, s35, s46
	v_or_b32_e32 v0, s35, v0
	v_mov_b32_e32 v1, s41
	s_addc_u32 s45, s41, s47
	v_lshl_add_u64 v[2:3], v[0:1], 0, s[52:53]
	v_lshl_add_u64 v[0:1], v[0:1], 0, s[50:51]
	s_add_u32 s40, s35, s48
	v_mov_b32_e32 v14, v195
	v_mov_b32_e32 v15, v195
	v_lshl_add_u64 v[172:173], v[162:163], 0, v[2:3]
	v_lshl_add_u64 v[174:175], v[162:163], 0, v[0:1]
	s_addc_u32 s41, s41, s49
	v_mov_b32_e32 v0, v195
	v_mov_b32_e32 v1, v195
	v_mov_b32_e32 v2, v195
	v_mov_b32_e32 v3, v195
	v_mov_b32_e32 v4, v195
	v_mov_b32_e32 v5, v195
	v_mov_b32_e32 v6, v195
	v_mov_b32_e32 v7, v195
	v_mov_b32_e32 v8, v195
	s_waitcnt lgkmcnt(0)
	v_mov_b32_e32 v9, v195
	v_mov_b32_e32 v10, v195
	v_mov_b32_e32 v11, v195
	v_mov_b32_e32 v12, v195
	v_mov_b32_e32 v13, v195
	v_mov_b32_e32 v169, 0
	v_mov_b64_e32 v[30:31], v[14:15]
	v_mov_b64_e32 v[46:47], v[14:15]
	v_mov_b64_e32 v[62:63], v[14:15]
	v_mov_b64_e32 v[78:79], v[14:15]
	v_readlane_b32 s70, v255, 6
	v_lshl_add_u32 v167, v182, 2, s55
	v_lshl_add_u64 v[178:179], v[164:165], 0, s[44:45]
	v_lshl_add_u64 v[180:181], v[164:165], 0, s[40:41]
	s_mov_b32 s51, 0
	s_mov_b64 s[40:41], -1
	s_mov_b64 s[46:47], 0
	v_add_u32_e32 v171, s55, v186
	v_mov_b64_e32 v[28:29], v[12:13]
	v_mov_b64_e32 v[26:27], v[10:11]
	v_mov_b64_e32 v[24:25], v[8:9]
	v_mov_b64_e32 v[22:23], v[6:7]
	v_mov_b64_e32 v[20:21], v[4:5]
	v_mov_b64_e32 v[18:19], v[2:3]
	v_mov_b64_e32 v[16:17], v[0:1]
	v_mov_b64_e32 v[44:45], v[12:13]
	v_mov_b64_e32 v[42:43], v[10:11]
	v_mov_b64_e32 v[40:41], v[8:9]
	v_mov_b64_e32 v[38:39], v[6:7]
	v_mov_b64_e32 v[36:37], v[4:5]
	v_mov_b64_e32 v[34:35], v[2:3]
	v_mov_b64_e32 v[32:33], v[0:1]
	v_mov_b64_e32 v[60:61], v[12:13]
	v_mov_b64_e32 v[58:59], v[10:11]
	v_mov_b64_e32 v[56:57], v[8:9]
	v_mov_b64_e32 v[54:55], v[6:7]
	v_mov_b64_e32 v[52:53], v[4:5]
	v_mov_b64_e32 v[50:51], v[2:3]
	v_mov_b64_e32 v[48:49], v[0:1]
	v_mov_b64_e32 v[76:77], v[12:13]
	v_mov_b64_e32 v[74:75], v[10:11]
	v_mov_b64_e32 v[72:73], v[8:9]
	v_mov_b64_e32 v[70:71], v[6:7]
	v_mov_b64_e32 v[68:69], v[4:5]
	v_mov_b64_e32 v[66:67], v[2:3]
	v_mov_b64_e32 v[64:65], v[0:1]
	s_mov_b32 s35, 0
	v_mov_b32_e32 v80, 0
	v_mov_b32_e32 v81, v169
	v_mov_b32_e32 v82, v169
	v_mov_b32_e32 v83, v169
	v_mov_b32_e32 v84, v169
	v_mov_b32_e32 v85, v169
	v_mov_b32_e32 v86, v169
	v_mov_b32_e32 v87, v169
	v_mov_b32_e32 v88, v169
	v_mov_b32_e32 v89, v169
	v_mov_b32_e32 v90, v169
	v_mov_b32_e32 v91, v169
	v_mov_b32_e32 v92, v169
	v_mov_b32_e32 v93, v169
	v_mov_b32_e32 v94, v169
	v_mov_b32_e32 v95, v169
	v_readlane_b32 s71, v255, 7
	s_cmp_gt_u32 s35, 2
	s_mov_b64 s[44:45], -1
	s_cbranch_scc0 .LBB0_129

; template <int DQK, int DV, bool BAND>
; DI void attn_unit(const AttnArgs& a, LAS unsigned char* lds, int tid) {
;     ...
;             vnext = vcur == 32768 ? 0 : vcur + 16384; const int vnn = vnext == 32768 ? 0 : vnext + 16384;
;             if (t + 2 < t_hi) AT_DMA(t + 2, vnn);
.LBB0_131:
	s_add_i32 s44, s51, 0x4000
	s_cmpk_lg_u32 s51, 0x8000
	s_cselect_b32 s50, s44, 0
	s_cmp_gt_u32 s35, 1
	s_cbranch_scc1 .LBB0_133
	s_add_i32 s44, s50, 0x4000
	s_cmpk_lg_u32 s50, 0x8000
	s_cselect_b32 s44, s44, 0
	s_add_i32 s44, s44, 0
	v_lshl_add_u64 v[96:97], v[178:179], 0, s[46:47]
	s_add_i32 s45, s44, s26
	s_mov_b32 m0, s45
	s_nop 0
	global_load_lds_dwordx4 v[96:97], off
	v_lshl_add_u64 v[96:97], v[180:181], 0, s[46:47]
	s_add_i32 s45, s44, s27
	s_mov_b32 m0, s45
	s_nop 0
	global_load_lds_dwordx4 v[96:97], off
	s_add_i32 s44, s44, 0xc000
	v_lshl_add_u64 v[96:97], v[174:175], 0, s[46:47]
	s_add_i32 s45, s44, s26
	s_mov_b32 m0, s45
	s_nop 0
	global_load_lds_dwordx4 v[96:97], off
	v_lshl_add_u64 v[96:97], v[172:173], 0, s[46:47]
	s_add_i32 s44, s44, s34
	s_mov_b32 m0, s44
	s_nop 0
	global_load_lds_dwordx4 v[96:97], off

.LBB0_174:
	s_lshl_b32 s83, s35, 10
	s_add_i32 s92, s83, 0
	s_mov_b32 m0, s92
	s_nop 0
	global_load_lds_dwordx4 v[4:5], off
	s_add_i32 s24, s35, 8
	s_cmp_lt_i32 s35, 4
	s_cselect_b32 s41, s24, s35
	s_cmp_gt_i32 s41, 7
	s_cselect_b64 s[48:49], -1, 0
	s_cmp_lt_i32 s41, 8
	s_cselect_b64 s[54:55], -1, 0
	s_lshl_b32 s24, s41, 3
	s_mov_b64 s[44:45], -1
	s_and_b64 vcc, exec, s[48:49]
	s_cbranch_vccnz .LBB0_176
	s_ashr_i32 s45, s24, 31
	s_mov_b32 s44, s24
	v_lshl_add_u64 v[4:5], s[44:45], 1, v[0:1]
	s_mov_b64 s[44:45], 0

.LBB0_178:
	s_lshl_b32 s88, s41, 10
	s_add_i32 s72, s88, 0
	s_cmp_lt_i32 s35, 4
	s_cbranch_scc0 .Ld_skip_t0
	s_mov_b32 m0, s72
	s_nop 0
	global_load_lds_dwordx4 v[4:5], off
.Ld_skip_t0:
	s_lshl_b32 s41, s35, 4
	s_and_b32 s95, s41, 48
	v_or_b32_e32 v0, s95, v182
	s_ashr_i32 s41, s52, 3
	s_and_b32 s52, s41, 0xffffffe0
	v_lshlrev_b32_e32 v194, 12, v0
	s_ashr_i32 s53, s52, 31
	v_lshl_add_u64 v[0:1], s[74:75], 0, v[194:195]
	v_lshl_add_u64 v[2:3], s[52:53], 1, v[0:1]
	v_lshlrev_b32_e32 v0, 1, v156
	v_mov_b32_e32 v1, v195
	v_lshl_add_u64 v[2:3], v[2:3], 0, v[0:1]
	v_lshl_add_u64 v[2:3], v[2:3], 0, s[28:29]
	s_add_i32 s89, s92, 0xc000
	s_mov_b32 m0, s89
	s_nop 0
	global_load_lds_dwordx4 v[2:3], off
	s_mov_b64 s[44:45], -1
	s_and_b64 vcc, exec, s[50:51]
	v_lshl_add_u64 v[4:5], s[74:75], 0, v[158:159]
	s_cbranch_vccz .LBB0_180
	s_ashr_i32 s41, s40, 31
	v_lshl_add_u64 v[6:7], s[40:41], 1, v[4:5]
	s_mov_b64 s[44:45], 0

; template <int DQK, int DV, bool BAND>
; DI void attn_unit(const AttnArgs& a, LAS unsigned char* lds, int tid) {
;     ...
;         if (t_lo + 1 < t_hi) AT_DMA(t_lo + 1, 16384);
.LBB0_182:
	s_add_i32 s41, s92, 0x4000
	s_mov_b32 m0, s41
	s_nop 0
	global_load_lds_dwordx4 v[6:7], off
	v_cndmask_b32_e64 v1, 0, 1, s[54:55]
	v_cmp_ne_u32_e64 s[44:45], 1, v1
	s_andn2_b64 vcc, exec, s[54:55]
	s_cbranch_vccnz .LBB0_184
	s_ashr_i32 s55, s24, 31
	s_mov_b32 s54, s24
	v_lshl_add_u64 v[4:5], s[54:55], 1, v[4:5]
	s_mov_b64 s[78:79], s[24:25]
	s_cbranch_execz .LBB0_185
	s_branch .LBB0_186

; #define AT_WAITBAR(N) asm volatile("s_waitcnt vmcnt(%0) lgkmcnt(0)\n\ts_barrier" :: "n"(N) : "memory")
; template <int DQK, int DV, bool BAND>
; DI void attn_unit(const AttnArgs& a, LAS unsigned char* lds, int tid) {
;     ...
;         if (t_lo + 1 < t_hi) AT_DMA(t_lo + 1, 16384);
;     ...
;             if (t + 1 < t_hi) AT_WAITBAR(NLD); else AT_WAITBAR(0);
.LBB0_186:
	s_lshl_b32 s24, s35, 8
	v_lshl_add_u64 v[2:3], s[74:75], 0, v[194:195]
	s_lshl_b64 s[70:71], s[52:53], 1
	s_add_i32 s24, s24, 0
	v_lshl_add_u64 v[2:3], v[2:3], 0, s[70:71]
	v_mov_b32_e32 v1, v195
	s_add_i32 s81, s24, 0x18000
	s_addk_i32 s72, 0x4000
	s_cmp_lt_i32 s35, 4
	s_cbranch_scc0 .Ld_skip_t1
	s_mov_b32 m0, s72
	s_nop 0
	global_load_lds_dwordx4 v[4:5], off
.Ld_skip_t1:
	v_lshl_add_u64 v[2:3], v[2:3], 0, v[0:1]
	s_mov_b64 s[52:53], 0x40080
	v_lshl_add_u64 v[2:3], v[2:3], 0, s[52:53]
	s_add_i32 s24, s92, 0x10000
	s_mov_b32 m0, s24
	s_nop 0
	global_load_lds_dwordx4 v[2:3], off
	s_ashr_i32 s41, s40, 31
	s_mov_b32 s24, s40
	s_lshl_b64 s[40:41], s[40:41], 1
	s_add_u32 s52, s74, s40
	s_addc_u32 s53, s75, s41
	s_lshl_b64 s[72:73], s[24:25], 1
	s_add_u32 s90, s76, s72
	s_addc_u32 s91, s77, s73
	s_lshl_b64 s[40:41], s[54:55], 1
	s_add_u32 s54, s74, s40
	s_addc_u32 s55, s75, s41
	s_lshl_b64 s[40:41], s[78:79], 1
	s_add_u32 s76, s76, s40
	s_addc_u32 s77, s77, s41
	s_add_u32 s74, s74, s70
	s_addc_u32 s75, s75, s71
	v_lshl_add_u64 v[0:1], s[74:75], 0, v[0:1]
	s_movk_i32 s74, 0xff80
	v_lshl_add_u64 v[2:3], s[90:91], 0, v[164:165]
	s_mov_b32 s75, -1
	v_lshl_add_u64 v[2:3], v[2:3], 0, s[74:75]
	v_lshl_add_u64 v[4:5], s[52:53], 0, v[162:163]
	s_cmp_lt_i32 s35, 4
	s_cbranch_scc0 .Ld_w0_hi
	s_waitcnt vmcnt(3) lgkmcnt(0)
	s_branch .Ld_w0_bar

; #define LAS __attribute__((address_space(3)))
; template <int DQK, int DV, bool BAND>
; DI void attn_unit(const AttnArgs& a, LAS unsigned char* lds, int tid) {
;     ...
;             if (t + 1 < t_hi) AT_WAITBAR(NLD); else AT_WAITBAR(0);
;             vnext = vcur == 32768 ? 0 : vcur + 16384; const int vnn = vnext == 32768 ? 0 : vnext + 16384;
;             if (t + 2 < t_hi) AT_DMA(t + 2, vnn);
;         }
;         bool active = true;
;         if (BAND) active = (64 * t + 63 >= qw - 64) && (64 * t <= qw + 95);
;         if (active) {
;             f32x16 p0, p1;
;             const LAS unsigned char* kb = lds + KBUF + vcur + hi * 1024 + r32 * 16;
; #pragma unroll
;             for (int dg = 0; dg < ND0; dg += KG) {
;                 bf16x8 kf0[KG], kf1[KG];
; #pragma unroll
;                 for (int j = 0; j < KG; ++j) if (dg + j < ND0) { kf0[j] = *(const LAS bf16x8*)(kb + (dg + j) * 2048); kf1[j] = *(const LAS bf16x8*)(kb + (dg + j) * 2048 + 512); }
;                 __builtin_amdgcn_sched_barrier(0);
; #pragma unroll
;                 for (int j = 0; j < KG; ++j) if (dg + j < ND0) {
;                     if (dg + j == 0) { p0 = MFMA32(kf0[j], qf[0], negm); p1 = MFMA32(kf1[j], qf[0], negm); }
;                     else { p0 = MFMA32(kf0[j], qf[dg + j], p0); p1 = MFMA32(kf1[j], qf[dg + j], p1); }
;                 }
;             }
;             s16x4 vlo[8], vhi[8];
;             if (VPRE) { const LAS unsigned char* vp_ = lds + VBUF + vcur + ((lane >> 4) & 1) * 32 + (lane & 3) * 8 + (4 * hi + ((lane & 15) >> 2)) * 64;
; #pragma unroll
;               for (int d = 0; d < 2; ++d)
; #pragma unroll
;                   for (int ks = 0; ks < 4; ++ks) { vlo[d * 4 + ks] = vtr(vp_ + d * 4096 + ks * 1024); vhi[d * 4 + ks] = vtr(vp_ + d * 4096 + ks * 1024 + 512); } }
;             __builtin_amdgcn_sched_barrier(0);
;             if (BAND) { const int qi = qw + r32; const int kb0 = 64 * t + 4 * hi;
; #pragma unroll
;                 for (int r = 0; r < 16; ++r) { const int kv = kb0 + (r & 3) + 8 * (r >> 2); int d = qi - kv; d = d < 0 ? -d : d; if (d > 64) p0[r] = -1e30f; int d2 = qi - kv - 32; d2 = d2 < 0 ? -d2 : d2; if (d2 > 64) p1[r] = -1e30f; } }
;             if (!a.nomax) {
;             float mx = fmaxf(p0[0], p1[0]);
; #pragma unroll
;             for (int r = 1; r < 16; ++r) mx = fmaxf(fmaxf(mx, p0[r]), p1[r]);
.Ld_w0_bar:
	s_barrier
	v_cndmask_b32_e64 v3, v5, v3, s[46:47]
	v_cndmask_b32_e64 v2, v4, v2, s[46:47]
	s_add_i32 s24, 0, 0x8000
	s_add_i32 s46, s83, s24
	s_mov_b32 m0, s46
	s_nop 0
	global_load_lds_dwordx4 v[2:3], off
	v_lshl_add_u64 v[2:3], s[76:77], 0, v[164:165]
	v_lshl_add_u64 v[2:3], v[2:3], 0, s[74:75]
	v_lshl_add_u64 v[4:5], s[54:55], 0, v[162:163]
	v_cndmask_b32_e64 v3, v5, v3, s[48:49]
	v_cndmask_b32_e64 v2, v4, v2, s[48:49]
	s_add_i32 s24, s88, s24
	s_cmp_lt_i32 s35, 4
	s_cbranch_scc0 .Ld_skip_t2
	s_mov_b32 m0, s24
	s_nop 0
	global_load_lds_dwordx4 v[2:3], off
.Ld_skip_t2:
	v_lshl_add_u64 v[0:1], v[0:1], 0, v[194:195]
	s_mov_b64 s[46:47], 0x80080
	v_lshl_add_u64 v[0:1], v[0:1], 0, s[46:47]
	s_add_i32 s92, s92, 0x14000
	s_mov_b32 m0, s92
	s_nop 0
	global_load_lds_dwordx4 v[0:1], off
	ds_read_b128 v[0:3], v183
	ds_read_b128 v[20:23], v183 offset:512
	ds_read_b128 v[24:27], v183 offset:2048
	ds_read_b128 v[28:31], v183 offset:2560
	ds_read_b128 v[32:35], v183 offset:4096
	ds_read_b128 v[36:39], v183 offset:4608
	ds_read_b128 v[40:43], v183 offset:6144
	ds_read_b128 v[44:47], v183 offset:6656
	s_movk_i32 s49, 0x4000
	s_mov_b32 s46, 1
	v_lshl_add_u32 v171, v157, 2, s81
	v_lshl_add_u32 v173, v184, 2, s81
	s_waitcnt lgkmcnt(7)
	v_mfma_f32_32x32x16_bf16 v[4:19], v[0:3], v[96:99], 0
	s_waitcnt lgkmcnt(6)
	v_mfma_f32_32x32x16_bf16 v[48:63], v[20:23], v[96:99], 0
	s_waitcnt lgkmcnt(5)
	v_mfma_f32_32x32x16_bf16 v[4:19], v[24:27], v[100:103], v[4:19]
	s_waitcnt lgkmcnt(4)
	v_mfma_f32_32x32x16_bf16 v[48:63], v[28:31], v[100:103], v[48:63]
	ds_read_b128 v[0:3], v183 offset:8192
	ds_read_b128 v[20:23], v183 offset:8704
	ds_read_b128 v[24:27], v183 offset:10240
	ds_read_b128 v[28:31], v183 offset:10752
	s_waitcnt lgkmcnt(7)
	v_mfma_f32_32x32x16_bf16 v[4:19], v[32:35], v[104:107], v[4:19]
	s_waitcnt lgkmcnt(6)
	v_mfma_f32_32x32x16_bf16 v[48:63], v[36:39], v[104:107], v[48:63]
	s_waitcnt lgkmcnt(5)
	v_mfma_f32_32x32x16_bf16 v[4:19], v[40:43], v[108:111], v[4:19]
	s_waitcnt lgkmcnt(4)
	v_mfma_f32_32x32x16_bf16 v[48:63], v[44:47], v[108:111], v[48:63]
	s_waitcnt lgkmcnt(3)
	v_mfma_f32_32x32x16_bf16 v[4:19], v[0:3], v[112:115], v[4:19]
	s_waitcnt lgkmcnt(2)
	v_mfma_f32_32x32x16_bf16 v[48:63], v[20:23], v[112:115], v[48:63]
	ds_read_b64_tr_b16 v[0:1], v185 offset:49152
	ds_read_b64_tr_b16 v[2:3], v185 offset:49664
	ds_read_b64_tr_b16 v[64:65], v185 offset:50176
	ds_read_b64_tr_b16 v[66:67], v185 offset:50688
	ds_read_b64_tr_b16 v[68:69], v185 offset:51200
	ds_read_b64_tr_b16 v[70:71], v185 offset:51712
	ds_read_b64_tr_b16 v[72:73], v185 offset:52224
	ds_read_b64_tr_b16 v[74:75], v185 offset:52736
	ds_read_b64_tr_b16 v[20:21], v185 offset:53248
	ds_read_b64_tr_b16 v[22:23], v185 offset:53760
	ds_read_b64_tr_b16 v[76:77], v185 offset:54272
	ds_read_b64_tr_b16 v[78:79], v185 offset:54784
	ds_read_b64_tr_b16 v[80:81], v185 offset:55296
	ds_read_b64_tr_b16 v[82:83], v185 offset:55808
	ds_read_b64_tr_b16 v[84:85], v185 offset:56320
	ds_read_b64_tr_b16 v[86:87], v185 offset:56832
	s_waitcnt lgkmcnt(14)
	v_mfma_f32_32x32x16_bf16 v[4:19], v[24:27], v[116:119], v[4:19]
	v_mfma_f32_32x32x16_bf16 v[48:63], v[28:31], v[116:119], v[48:63]
	s_nop 11
	v_max_f32_e32 v24, v48, v48
	v_max_f32_e32 v25, v4, v4
	v_max_f32_e32 v24, v25, v24
	v_max3_f32 v24, v24, v5, v49
	v_max3_f32 v24, v24, v6, v50
	v_max3_f32 v24, v24, v7, v51
	v_max3_f32 v24, v24, v8, v52
	v_max3_f32 v24, v24, v9, v53
	v_max3_f32 v24, v24, v10, v54
	v_max3_f32 v24, v24, v11, v55
	v_max3_f32 v24, v24, v12, v56
	v_max3_f32 v24, v24, v13, v57
	v_max3_f32 v24, v24, v14, v58
	v_max3_f32 v24, v24, v15, v59
	v_max3_f32 v24, v24, v16, v60
	v_max3_f32 v24, v24, v17, v61
	v_max3_f32 v24, v24, v18, v62
	v_max3_f32 v24, v24, v19, v63
	v_mov_b32_e32 v25, v24
	s_nop 1
	v_permlane32_swap_b32_e32 v24, v25
	s_mov_b32 s24, 0xc61c4000
	v_max3_f32 v120, v24, v25, s24
	v_sub_f32_e32 v4, v4, v120
	v_sub_f32_e32 v5, v5, v120
	v_sub_f32_e32 v6, v6, v120
	v_sub_f32_e32 v7, v7, v120
	v_sub_f32_e32 v8, v8, v120
	v_sub_f32_e32 v9, v9, v120
	v_sub_f32_e32 v10, v10, v120
	v_sub_f32_e32 v11, v11, v120
	v_exp_f32_e32 v4, v4
	v_exp_f32_e32 v5, v5
	v_exp_f32_e32 v6, v6
	v_exp_f32_e32 v7, v7
	v_exp_f32_e32 v8, v8
	v_exp_f32_e32 v9, v9
	v_exp_f32_e32 v10, v10
	v_exp_f32_e32 v11, v11
	v_cvt_pk_bf16_f32 v32, v4, v5
	v_cvt_pk_bf16_f32 v33, v6, v7
	v_cvt_pk_bf16_f32 v34, v8, v9
	v_cvt_pk_bf16_f32 v35, v10, v11
	v_add_f32_e32 v46, v4, v5
	v_add_f32_e32 v47, v6, v7
	v_add_f32_e32 v46, v46, v8
	v_add_f32_e32 v47, v47, v9
	v_add_f32_e32 v46, v46, v10
	v_add_f32_e32 v47, v47, v11
	v_sub_f32_e32 v24, v12, v120
	v_sub_f32_e32 v25, v13, v120
	v_exp_f32_e32 v41, v24
	v_exp_f32_e32 v42, v25
	v_sub_f32_e32 v26, v14, v120
	v_sub_f32_e32 v36, v15, v120
	v_sub_f32_e32 v37, v16, v120
	v_sub_f32_e32 v38, v17, v120
	v_sub_f32_e32 v39, v18, v120
	v_sub_f32_e32 v40, v19, v120
	v_exp_f32_e32 v89, v26
	v_exp_f32_e32 v90, v36
	v_exp_f32_e32 v91, v37
	v_exp_f32_e32 v121, v38
	v_exp_f32_e32 v122, v39
	v_exp_f32_e32 v123, v40
	v_mfma_f32_32x32x16_bf16 v[0:15], v[32:35], v[0:3], 0
	v_add_f32_e32 v46, v46, v41
	v_add_f32_e32 v47, v47, v42
	v_add_f32_e32 v46, v46, v89
	v_add_f32_e32 v47, v47, v90
	v_add_f32_e32 v46, v46, v91
	v_add_f32_e32 v47, v47, v121
	v_add_f32_e32 v46, v46, v122
	v_add_f32_e32 v47, v47, v123
	v_cvt_pk_bf16_f32 v88, v41, v42
	v_cvt_pk_bf16_f32 v89, v89, v90
	v_cvt_pk_bf16_f32 v90, v91, v121
	v_cvt_pk_bf16_f32 v91, v122, v123
	v_sub_f32_e32 v48, v48, v120
	v_sub_f32_e32 v49, v49, v120
	v_sub_f32_e32 v50, v50, v120
	s_waitcnt lgkmcnt(6)
; #define LAS __attribute__((address_space(3)))
; template <int DQK, int DV, bool BAND>
; DI void attn_unit(const AttnArgs& a, LAS unsigned char* lds, int tid) {
;     ...
;                 for (int r = 0; r < 16; ++r) { p0[r] -= delta; p1[r] -= delta; negm[r] = -m_run; }
;                 if (!first) {
;                     const float alpha = __builtin_amdgcn_exp2f(-delta);
;                     if (hi == 0) scr[r32] = alpha;
; #pragma unroll
;                     for (int g = 0; g < 4; ++g) { const f32x4 al = *(const LAS f32x4*)(scr + 8 * g + 4 * hi);
;                         lacc[4 * g] *= al.x; lacc[4 * g + 1] *= al.y; lacc[4 * g + 2] *= al.z; lacc[4 * g + 3] *= al.w;
; #pragma unroll
;                         for (int d = 0; d < NDB; ++d) { o[d][4 * g] *= al.x; o[d][4 * g + 1] *= al.y; o[d][4 * g + 2] *= al.z; o[d][4 * g + 3] *= al.w; } }
;                 }
;                 first = false;
;             }
;             }
; #pragma unroll
;             for (int r = 0; r < 16; ++r) { p0[r] = __builtin_amdgcn_exp2f(p0[r]); p1[r] = __builtin_amdgcn_exp2f(p1[r]); }
;             { u32x4 w;
;               w.x = pk2(p0[0], p0[1]); w.y = pk2(p0[2], p0[3]); w.z = pk2(p0[4], p0[5]); w.w = pk2(p0[6], p0[7]); pa[0] = __builtin_bit_cast(bf16x8, w);
;               w.x = pk2(p0[8], p0[9]); w.y = pk2(p0[10], p0[11]); w.z = pk2(p0[12], p0[13]); w.w = pk2(p0[14], p0[15]); pa[1] = __builtin_bit_cast(bf16x8, w);
;               w.x = pk2(p1[0], p1[1]); w.y = pk2(p1[2], p1[3]); w.z = pk2(p1[4], p1[5]); w.w = pk2(p1[6], p1[7]); pa[2] = __builtin_bit_cast(bf16x8, w);
;               w.x = pk2(p1[8], p1[9]); w.y = pk2(p1[10], p1[11]); w.z = pk2(p1[12], p1[13]); w.w = pk2(p1[14], p1[15]); pa[3] = __builtin_bit_cast(bf16x8, w); }
;             if (DQK > 96) { AT_PV(vcur); } else {
;                 if (!VPRE) { const LAS unsigned char* vp_ = lds + VBUF + vcur + ((lane >> 4) & 1) * 32 + (lane & 3) * 8 + (4 * hi + ((lane & 15) >> 2)) * 64;
; #pragma unroll
;                     for (int d = 0; d < 2; ++d)
; #pragma unroll
;                         for (int ks = 0; ks < 4; ++ks) { vlo[d * 4 + ks] = vtr(vp_ + d * 4096 + ks * 1024); vhi[d * 4 + ks] = vtr(vp_ + d * 4096 + ks * 1024 + 512); }
;                     __builtin_amdgcn_sched_barrier(0); }
; #pragma unroll
;                 for (int ks = 0; ks < 4; ++ks) {
; #pragma unroll
	v_mfma_f32_32x32x16_bf16 v[16:31], v[32:35], v[20:23], 0
	v_sub_f32_e32 v51, v51, v120
	v_sub_f32_e32 v52, v52, v120
	v_sub_f32_e32 v53, v53, v120
	v_sub_f32_e32 v54, v54, v120
	v_sub_f32_e32 v55, v55, v120
	v_exp_f32_e32 v48, v48
	v_exp_f32_e32 v49, v49
	v_exp_f32_e32 v50, v50
	v_exp_f32_e32 v51, v51
	v_exp_f32_e32 v52, v52
	v_exp_f32_e32 v53, v53
	v_exp_f32_e32 v54, v54
	v_exp_f32_e32 v55, v55
	v_add_f32_e32 v46, v46, v48
	v_add_f32_e32 v47, v47, v49
	v_add_f32_e32 v46, v46, v50
	v_add_f32_e32 v47, v47, v51
	v_add_f32_e32 v46, v46, v52
	v_add_f32_e32 v47, v47, v53
	v_add_f32_e32 v46, v46, v54
	v_add_f32_e32 v47, v47, v55
	v_cvt_pk_bf16_f32 v48, v48, v49
	v_mfma_f32_32x32x16_bf16 v[0:15], v[88:91], v[64:67], v[0:15]
	v_cvt_pk_bf16_f32 v49, v50, v51
	v_cvt_pk_bf16_f32 v50, v52, v53
	v_cvt_pk_bf16_f32 v51, v54, v55
	v_sub_f32_e32 v52, v56, v120
	v_sub_f32_e32 v53, v57, v120
	v_sub_f32_e32 v54, v58, v120
	v_sub_f32_e32 v55, v59, v120
	s_waitcnt lgkmcnt(4)
	v_mfma_f32_32x32x16_bf16 v[16:31], v[88:91], v[76:79], v[16:31]
	v_sub_f32_e32 v56, v60, v120
	v_sub_f32_e32 v57, v61, v120
	v_sub_f32_e32 v58, v62, v120
	v_sub_f32_e32 v59, v63, v120
	v_exp_f32_e32 v52, v52
	v_exp_f32_e32 v53, v53
	v_exp_f32_e32 v54, v54
	v_exp_f32_e32 v55, v55
	v_exp_f32_e32 v56, v56
	v_exp_f32_e32 v57, v57
	v_exp_f32_e32 v58, v58
	v_exp_f32_e32 v59, v59
	v_add_f32_e32 v46, v46, v52
	v_add_f32_e32 v47, v47, v53
	v_add_f32_e32 v46, v46, v54
	v_add_f32_e32 v47, v47, v55
	v_add_f32_e32 v46, v46, v56
	v_add_f32_e32 v47, v47, v57
	v_add_f32_e32 v46, v46, v58
	v_add_f32_e32 v47, v47, v59
	v_cvt_pk_bf16_f32 v52, v52, v53
	v_cvt_pk_bf16_f32 v53, v54, v55
	v_mfma_f32_32x32x16_bf16 v[0:15], v[48:51], v[68:71], v[0:15]
	v_cvt_pk_bf16_f32 v54, v56, v57
	v_cvt_pk_bf16_f32 v55, v58, v59
	s_add_u32 s24, s70, s66
	s_addc_u32 s47, s71, s67
	s_add_u32 s56, s24, s56
	s_addc_u32 s57, s47, s57
	s_add_u32 s40, s64, s40
	s_waitcnt lgkmcnt(2)
	v_mfma_f32_32x32x16_bf16 v[16:31], v[48:51], v[80:83], v[16:31]
	s_addc_u32 s41, s65, s41
	v_add_f32_e32 v200, 0, v120
	v_add_lshl_u32 v194, v182, s95, 12
	v_lshl_add_u64 v[178:179], v[168:169], 0, s[40:41]
	s_add_u32 s40, s64, s72
	s_addc_u32 s41, s65, s73
	v_readlane_b32 s72, v255, 4
	v_xor_b32_e32 v48, 0x80000000, v200
	v_lshl_add_u64 v[50:51], s[56:57], 0, v[194:195]
	v_lshl_add_u64 v[174:175], v[166:167], 0, v[50:51]
	v_lshl_add_u64 v[180:181], v[168:169], 0, s[40:41]
	s_mov_b32 s47, 3
	v_mov_b32_e32 v49, v48
	v_mov_b32_e32 v50, v48
	v_mfma_f32_32x32x16_bf16 v[0:15], v[52:55], v[72:75], v[0:15]
	v_mov_b32_e32 v51, v48
	v_mov_b32_e32 v56, v48
	v_mov_b32_e32 v57, v48
	v_mov_b32_e32 v58, v48
	v_mov_b32_e32 v59, v48
	v_mov_b32_e32 v60, v48
	v_mov_b32_e32 v61, v48
	s_waitcnt lgkmcnt(0)
	v_mfma_f32_32x32x16_bf16 v[16:31], v[52:55], v[84:87], v[16:31]
	v_mov_b32_e32 v62, v48
	v_mov_b32_e32 v63, v48
	v_readlane_b32 s64, v253, 57
	v_readlane_b32 s67, v253, 59
	v_readlane_b32 s66, v253, 60
	s_movk_i32 s95, 0xc00
	s_mov_b32 s90, 0x41000000
	v_mov_b32_e32 v52, v48
	v_mov_b32_e32 v53, v48
	v_mov_b32_e32 v54, v48
	v_mov_b32_e32 v55, v48
	s_mov_b64 s[70:71], 0x1000
	s_mov_b64 s[74:75], 0x60000
	s_mov_b64 s[76:77], 0x30000
	v_readlane_b32 s91, v254, 40
	v_readlane_b32 s73, v255, 5
	v_readlane_b32 s65, v253, 58
	s_add_i32 s24, s47, -1
	s_cmp_ge_u32 s24, s69
	s_mov_b64 s[40:41], -1
	s_cbranch_scc0 .LBB0_188

; template <int DQK, int DV, bool BAND>
; DI void attn_unit(const AttnArgs& a, LAS unsigned char* lds, int tid) {
;     ...
;             vnext = vcur == 32768 ? 0 : vcur + 16384; const int vnn = vnext == 32768 ? 0 : vnext + 16384;
;             if (t + 2 < t_hi) AT_DMA(t + 2, vnn);
.LBB0_193:
	s_add_i32 s24, s48, 0x4000
	s_cmpk_lg_u32 s48, 0x8000
	s_cselect_b32 s24, s24, 0
	s_add_i32 s40, s24, 0
	s_add_i32 s41, s40, s83
	s_mov_b32 m0, s41
	s_nop 0
	global_load_lds_dwordx4 v[66:67], off
	s_and_b64 vcc, exec, s[44:45]
	v_mov_b64_e32 v[66:67], v[178:179]
	s_cbranch_vccnz .LBB0_195
	v_lshl_add_u64 v[66:67], s[54:55], 0, v[64:65]
.LBB0_195:
	s_add_i32 s40, s40, s88
	s_cmp_lt_i32 s35, 4
	s_cbranch_scc0 .Ld_skip_lp
	s_mov_b32 m0, s40
	s_nop 0
	global_load_lds_dwordx4 v[66:67], off
.Ld_skip_lp:
	s_add_i32 s24, s89, s24
	s_mov_b32 m0, s24
	s_nop 0
	global_load_lds_dwordx4 v[174:175], off

; #define AT_WAITBAR(N) asm volatile("s_waitcnt vmcnt(%0) lgkmcnt(0)\n\ts_barrier" :: "n"(N) : "memory")
; template <int DQK, int DV, bool BAND>
; DI void attn_unit(const AttnArgs& a, LAS unsigned char* lds, int tid) {
;     ...
;     if (wid >= 4) __builtin_amdgcn_s_setprio(1);
;     f32x16 o[NDB], lacc, negm;
; #pragma unroll
;     for (int d = 0; d < NDB; ++d)
; #pragma unroll
;         for (int r = 0; r < 16; ++r) o[d][r] = 0.f;
; #pragma unroll
;     for (int r = 0; r < 16; ++r) { lacc[r] = 0.f; negm[r] = 0.f; }
;     float m_run = 0.f; bool first = true;
;     const bf16x8 ones = (bf16x8){(short)0x3F80, (short)0x3F80, (short)0x3F80, (short)0x3F80, (short)0x3F80, (short)0x3F80, (short)0x3F80, (short)0x3F80};
;     if (BAND) {
;         for (int t = t_lo; t < t_hi; ++t) AT_DMA(t, (t - t_lo) * 8192);
;         AT_WAITBAR(0);
;     } else {
;         AT_DMA(t_lo, 0);
;         if (t_lo + 1 < t_hi) AT_DMA(t_lo + 1, 16384);
;     }
; __global__ void __launch_bounds__(512, 2) mega_fwd(Params p) {
;     ...
;                         for (int u = vcu; u < nunits; u += G) {
;                             int r = u; const int qb = r % nqb; r /= nqb; const int hc = r % 16; const int sq = r / 16;
;                             const size_t row0 = (size_t)sq * S;
;                             AttnArgs a; a.nomax = 0; a.q = BIG + (row0 + qb * 256) * 3072 + hc * 64; a.qs = 3072; a.k = BIG + row0 * 3072 + 1024 + hc * 64; a.ks = 3072; a.k2 = nullptr; a.k2s = 0;
;                             a.v = BIG + row0 * 3072 + 2048 + (hc >> 1) * 128; a.vs = 3072; a.o = OC + (row0 + qb * 256) * 2048 + hc * 128; a.os = 2048; a.lse = nullptr; a.lses = 0;
;                             a.kv_len = S; a.q0 = qb * 256;
;                             attn_unit<64, 128, false>(a, lds, tid);
.LBB0_210:
	s_mul_i32 s24, s47, 0x1800
	s_mul_hi_u32 s26, s46, 0x1800
	s_add_i32 s56, s26, s24
	s_mul_i32 s57, s46, 0x1800
	s_add_u32 s24, s70, s57
	s_addc_u32 s49, s71, s56
	s_add_u32 s34, s24, s40
	s_addc_u32 s35, s49, s41
	s_and_b32 s26, s48, 0xffffff80
	s_ashr_i32 s27, s26, 31
	s_lshl_b64 s[46:47], s[26:27], 1
	s_add_u32 s24, s24, s46
	s_addc_u32 s26, s49, s47
	s_add_u32 s48, s24, 0x1000
	s_addc_u32 s49, s26, 0
	s_lshl_b32 s50, s19, 3
	s_lshl_b32 s24, s19, 8
	s_ashr_i32 s51, s50, 31
	s_add_i32 s24, s24, 0
	v_lshl_add_u64 v[0:1], s[34:35], 0, v[178:179]
	s_lshl_b64 s[52:53], s[50:51], 1
	s_add_i32 s64, s24, 0x18000
	v_lshl_add_u64 v[0:1], v[0:1], 0, s[52:53]
	s_mov_b64 s[26:27], 0x800
	s_lshl_b32 s24, s19, 10
	v_lshl_add_u64 v[0:1], v[0:1], 0, s[26:27]
	s_add_i32 s26, s24, 0
	s_mov_b32 m0, s26
	s_nop 0
	global_load_lds_dwordx4 v[0:1], off
	s_lshl_b32 s27, s19, 4
	s_andn2_b32 s50, s50, 31
	v_and_or_b32 v4, s27, 48, v203
	v_mov_b64_e32 v[0:1], s[48:49]
	s_movk_i32 s70, 0x1800
	s_ashr_i32 s51, s50, 31
	v_mad_u64_u32 v[0:1], s[54:55], v4, s70, v[0:1]
	s_lshl_b64 s[50:51], s[50:51], 1
	s_add_i32 s65, 0, 0xc000
	v_lshl_add_u64 v[2:3], v[0:1], 0, s[50:51]
	v_mov_b32_e32 v185, v195
	s_add_i32 s27, s24, s65
	v_lshl_add_u64 v[2:3], v[2:3], 0, v[184:185]
	s_mov_b32 m0, s27
	s_nop 0
	global_load_lds_dwordx4 v[2:3], off
	s_add_i32 s27, s19, 8
	s_lshl_b32 s54, s27, 3
	s_andn2_b32 s54, s54, 31
	s_ashr_i32 s55, s54, 31
	s_lshl_b64 s[54:55], s[54:55], 1
	v_lshl_add_u64 v[0:1], v[0:1], 0, s[54:55]
	v_lshl_add_u64 v[0:1], v[0:1], 0, v[184:185]
	s_lshl_b32 s27, s27, 10
	v_mov_b32_e32 v187, v195
	s_add_i32 s65, s27, s65
	s_mov_b32 m0, s65
	s_nop 0
	global_load_lds_dwordx4 v[0:1], off
	v_lshl_add_u64 v[0:1], s[34:35], 0, v[186:187]
	v_lshl_add_u64 v[0:1], v[0:1], 0, s[52:53]
	s_mov_b64 s[34:35], 0x60800
	v_lshl_add_u64 v[0:1], v[0:1], 0, s[34:35]
	s_add_i32 s34, s26, 0x4000
	s_mov_b32 m0, s34
	s_nop 0
	global_load_lds_dwordx4 v[0:1], off
	v_mul_u32_u24_e32 v0, 0xc00, v4
	v_lshlrev_b32_e32 v0, 1, v0
	v_mov_b32_e32 v1, v195
	v_lshl_add_u64 v[0:1], s[48:49], 0, v[0:1]
	v_lshl_add_u64 v[0:1], v[0:1], 0, s[74:75]
	s_add_i32 s34, 0, 0x10000
	v_lshl_add_u64 v[2:3], v[0:1], 0, s[50:51]
	s_add_i32 s35, s24, s34
	s_add_i32 s34, s27, s34
	v_lshl_add_u64 v[2:3], v[2:3], 0, v[184:185]
	s_mov_b32 m0, s35
	s_nop 0
	global_load_lds_dwordx4 v[2:3], off
	v_lshl_add_u64 v[0:1], v[0:1], 0, s[54:55]
	s_add_u32 s46, s46, s57
	v_lshl_add_u64 v[0:1], v[0:1], 0, v[184:185]
	s_mov_b32 m0, s34
	s_nop 0
	global_load_lds_dwordx4 v[0:1], off
	s_addc_u32 s47, s47, s56
	v_mov_b64_e32 v[0:1], s[46:47]
	s_add_u32 s35, s57, s40
	v_mad_u64_u32 v[0:1], s[46:47], v4, s70, v[0:1]
	s_addc_u32 s41, s56, s41
	v_lshl_add_u64 v[2:3], v[0:1], 0, s[50:51]
	v_lshl_add_u64 v[0:1], v[0:1], 0, s[54:55]
	s_add_u32 s40, s35, s52
	v_mov_b32_e32 v14, v195
	v_mov_b32_e32 v15, v195
	v_readlane_b32 s70, v255, 6
	v_lshl_add_u64 v[190:191], v[180:181], 0, v[2:3]
	v_lshl_add_u64 v[198:199], v[180:181], 0, v[0:1]
	s_addc_u32 s41, s41, s53
	v_mov_b32_e32 v0, v195
	v_mov_b32_e32 v1, v195
	v_mov_b32_e32 v2, v195
	v_mov_b32_e32 v3, v195
	v_mov_b32_e32 v4, v195
	v_mov_b32_e32 v5, v195
	v_mov_b32_e32 v6, v195
	v_mov_b32_e32 v7, v195
	v_mov_b32_e32 v8, v195
	v_mov_b32_e32 v9, v195
	v_mov_b32_e32 v10, v195
	v_mov_b32_e32 v11, v195
	v_mov_b32_e32 v12, v195
	v_mov_b32_e32 v13, v195
	v_mov_b32_e32 v189, 0
	v_mov_b64_e32 v[62:63], v[14:15]
	v_mov_b64_e32 v[46:47], v[14:15]
	v_mov_b64_e32 v[30:31], v[14:15]
	v_mov_b64_e32 v[78:79], v[14:15]
	s_mov_b32 s34, 2
	v_lshl_add_u32 v185, v196, 2, s64
	v_lshl_add_u32 v187, v206, 2, s64
	v_readlane_b32 s71, v255, 7
	v_lshl_add_u64 v[200:201], v[182:183], 0, s[40:41]
	s_mov_b32 s48, 0
	s_mov_b64 s[40:41], -1
	v_mov_b64_e32 v[60:61], v[12:13]
	v_mov_b64_e32 v[58:59], v[10:11]
	v_mov_b64_e32 v[56:57], v[8:9]
	v_mov_b64_e32 v[54:55], v[6:7]
	v_mov_b64_e32 v[52:53], v[4:5]
	v_mov_b64_e32 v[50:51], v[2:3]
	v_mov_b64_e32 v[48:49], v[0:1]
	v_mov_b64_e32 v[44:45], v[12:13]
	v_mov_b64_e32 v[42:43], v[10:11]
	v_mov_b64_e32 v[40:41], v[8:9]
	v_mov_b64_e32 v[38:39], v[6:7]
	v_mov_b64_e32 v[36:37], v[4:5]
	v_mov_b64_e32 v[34:35], v[2:3]
	v_mov_b64_e32 v[32:33], v[0:1]
	v_mov_b64_e32 v[28:29], v[12:13]
	v_mov_b64_e32 v[26:27], v[10:11]
	v_mov_b64_e32 v[24:25], v[8:9]
	v_mov_b64_e32 v[22:23], v[6:7]
	v_mov_b64_e32 v[20:21], v[4:5]
	v_mov_b64_e32 v[18:19], v[2:3]
	v_mov_b64_e32 v[16:17], v[0:1]
	v_mov_b64_e32 v[76:77], v[12:13]
	v_mov_b64_e32 v[74:75], v[10:11]
	v_mov_b64_e32 v[72:73], v[8:9]
	v_mov_b64_e32 v[70:71], v[6:7]
	v_mov_b64_e32 v[68:69], v[4:5]
	v_mov_b64_e32 v[66:67], v[2:3]
	v_mov_b64_e32 v[64:65], v[0:1]
	v_mov_b32_e32 v80, 0
	v_mov_b32_e32 v81, v189
	v_mov_b32_e32 v82, v189
	v_mov_b32_e32 v83, v189
	v_mov_b32_e32 v84, v189
	v_mov_b32_e32 v85, v189
	v_mov_b32_e32 v86, v189
	v_mov_b32_e32 v87, v189
	v_mov_b32_e32 v88, v189
	v_mov_b32_e32 v89, v189
	v_mov_b32_e32 v90, v189
	v_mov_b32_e32 v91, v189
	v_mov_b32_e32 v92, v189
	v_mov_b32_e32 v93, v189
	v_mov_b32_e32 v94, v189
	v_mov_b32_e32 v95, v189
	v_readlane_b32 s64, v253, 57
	v_readlane_b32 s66, v253, 60
	v_readlane_b32 s65, v253, 58
	s_add_i32 s35, s34, -1
	s_cmp_ge_u32 s35, s69
	s_mov_b64 s[46:47], -1
	s_cbranch_scc0 .LBB0_212

; template <int DQK, int DV, bool BAND>
; DI void attn_unit(const AttnArgs& a, LAS unsigned char* lds, int tid) {
;     ...
;             vnext = vcur == 32768 ? 0 : vcur + 16384; const int vnn = vnext == 32768 ? 0 : vnext + 16384;
;             if (t + 2 < t_hi) AT_DMA(t + 2, vnn);
.LBB0_214:
	s_add_i32 s35, s48, 0x4000
	s_cmpk_lg_u32 s48, 0x8000
	s_cselect_b32 s35, s35, 0
	s_cmp_ge_u32 s34, s69
	s_cbranch_scc1 .LBB0_216
	s_add_i32 s46, s35, 0x4000
	s_cmpk_lg_u32 s35, 0x8000
	s_cselect_b32 s46, s46, 0
	s_add_i32 s47, s26, s46
	s_add_i32 s46, s46, 0
	s_mov_b32 m0, s47
	s_nop 0
	global_load_lds_dwordx4 v[200:201], off
	s_add_i32 s46, s46, 0xc000
	s_add_i32 s47, s46, s24
	s_mov_b32 m0, s47
	s_nop 0
	global_load_lds_dwordx4 v[190:191], off
	s_add_i32 s46, s46, s27
	s_mov_b32 m0, s46
	s_nop 0
	global_load_lds_dwordx4 v[198:199], off

; #define AT_WAITBAR(N) asm volatile("s_waitcnt vmcnt(%0) lgkmcnt(0)\n\ts_barrier" :: "n"(N) : "memory")
; template <int DQK, int DV, bool BAND>
; DI void attn_unit(const AttnArgs& a, LAS unsigned char* lds, int tid) {
;     ...
;     if (wid >= 4) __builtin_amdgcn_s_setprio(1);
;     f32x16 o[NDB], lacc, negm;
; #pragma unroll
;     for (int d = 0; d < NDB; ++d)
; #pragma unroll
;         for (int r = 0; r < 16; ++r) o[d][r] = 0.f;
; #pragma unroll
;     for (int r = 0; r < 16; ++r) { lacc[r] = 0.f; negm[r] = 0.f; }
;     float m_run = 0.f; bool first = true;
;     const bf16x8 ones = (bf16x8){(short)0x3F80, (short)0x3F80, (short)0x3F80, (short)0x3F80, (short)0x3F80, (short)0x3F80, (short)0x3F80, (short)0x3F80};
;     if (BAND) {
;         for (int t = t_lo; t < t_hi; ++t) AT_DMA(t, (t - t_lo) * 8192);
;         AT_WAITBAR(0);
;     } else {
;         AT_DMA(t_lo, 0);
;         if (t_lo + 1 < t_hi) AT_DMA(t_lo + 1, 16384);
;     }
; __global__ void __launch_bounds__(512, 2) mega_fwd(Params p) {
;     ...
;                             int r = u; const int qb = r % nqb; r /= nqb; const int h = r % 16; const int sq = r / 16;
;                             const size_t row0 = (size_t)sq * S;
;                             AttnArgs a; a.nomax = 0; a.q = BIG + (row0 + qb * 256) * 1536 + h * 64; a.qs = 1536; a.k = BIG + row0 * 1536 + 1024 + (h >> 2) * 64; a.ks = 1536; a.k2 = nullptr; a.k2s = 0;
;                             a.v = BIG + row0 * 1536 + 1280 + (h >> 2) * 64; a.vs = 1536; a.o = AO + (row0 + qb * 256) * 1024 + h * 64; a.os = 1024; a.lse = nullptr; a.lses = 0;
;                             a.kv_len = S; a.q0 = qb * 256; a.nomax = lamp[1] <= 40.0f ? 1 : 0;
;                             attn_unit<64, 64, false>(a, lds, tid);
.LBB0_237:
	s_mul_i32 s19, s41, 0xc00
	s_mul_hi_u32 s24, s40, 0xc00
	s_add_i32 s24, s24, s19
	s_mul_i32 s52, s40, 0xc00
	s_add_u32 s19, s70, s52
	s_addc_u32 s35, s71, s24
	s_lshl_b32 s17, s17, 4
	s_and_b32 s26, s17, 0xffffffc0
	s_ashr_i32 s27, s26, 31
	s_lshl_b64 s[26:27], s[26:27], 1
	s_add_u32 s34, s19, s26
	s_addc_u32 s35, s35, s27
	s_lshl_b32 s40, s16, 3
	s_mov_b32 s17, 0x42200000
	s_ashr_i32 s41, s40, 31
	s_waitcnt lgkmcnt(0)
	v_cmp_nge_f32_e64 s[44:45], s17, v0
	s_lshl_b32 s17, s16, 8
	v_lshl_add_u64 v[0:1], s[34:35], 0, v[144:145]
	s_lshl_b64 s[40:41], s[40:41], 1
	s_add_i32 s17, s17, 0
	v_lshl_add_u64 v[0:1], v[0:1], 0, s[40:41]
	s_mov_b64 s[48:49], 0x800
	s_lshl_b32 s50, s16, 10
	s_add_i32 s53, s17, 0x18000
	v_lshl_add_u64 v[0:1], v[0:1], 0, s[48:49]
	s_add_i32 s17, s50, 0
	s_mov_b32 m0, s17
	s_nop 0
	global_load_lds_dwordx4 v[0:1], off
	s_lshl_b32 s19, s16, 4
	s_ashr_i32 s18, s18, 3
	v_and_or_b32 v2, s19, 48, v161
	s_andn2_b32 s18, s18, 31
	v_mov_b64_e32 v[0:1], s[34:35]
	s_ashr_i32 s19, s18, 31
	v_mad_u64_u32 v[0:1], s[48:49], v2, s95, v[0:1]
	s_lshl_b64 s[48:49], s[18:19], 1
	s_nop 0
	v_lshl_add_u64 v[0:1], v[0:1], 0, s[48:49]
	v_mov_b32_e32 v151, v195
	v_lshl_add_u64 v[0:1], v[0:1], 0, v[150:151]
	s_mov_b64 s[18:19], 0xa00
	v_lshl_add_u64 v[0:1], v[0:1], 0, s[18:19]
	s_add_i32 s18, 0, 0xc000
	v_mov_b32_e32 v153, v195
	s_add_i32 s18, s50, s18
	s_mov_b32 m0, s18
	s_nop 0
	global_load_lds_dwordx4 v[0:1], off
	v_lshl_add_u64 v[0:1], s[34:35], 0, v[152:153]
	v_lshl_add_u64 v[0:1], v[0:1], 0, s[40:41]
	s_mov_b64 s[50:51], 0x30800
	v_lshl_add_u64 v[0:1], v[0:1], 0, s[50:51]
	s_add_i32 s19, s17, 0x4000
	s_mov_b32 m0, s19
	s_nop 0
	global_load_lds_dwordx4 v[0:1], off
	v_mul_u32_u24_e32 v0, 0x600, v2
	v_lshlrev_b32_e32 v0, 1, v0
	v_mov_b32_e32 v1, v195
	v_lshl_add_u64 v[0:1], s[34:35], 0, v[0:1]
	v_lshl_add_u64 v[0:1], v[0:1], 0, s[48:49]
	v_lshl_add_u64 v[0:1], v[0:1], 0, v[150:151]
	s_mov_b64 s[34:35], 0x30a00
	s_add_i32 s19, s17, 0x10000
	v_lshl_add_u64 v[0:1], v[0:1], 0, s[34:35]
	s_mov_b32 m0, s19
	s_nop 0
	global_load_lds_dwordx4 v[0:1], off
	s_add_u32 s19, s48, s26
	s_addc_u32 s35, s49, s27
	s_add_u32 s34, s19, s52
	s_addc_u32 s35, s35, s24
	s_add_u32 s19, s52, s26
	s_addc_u32 s24, s24, s27
	v_mov_b64_e32 v[0:1], s[34:35]
	s_add_u32 s26, s19, s40
	v_mad_u64_u32 v[0:1], s[34:35], v2, s95, v[0:1]
	s_addc_u32 s27, s24, s41
	v_mov_b32_e32 v155, 0
	v_lshl_add_u32 v151, v160, 2, s53
	v_lshl_add_u32 v153, v163, 2, s53
	v_lshl_add_u64 v[156:157], v[146:147], 0, v[0:1]
	v_lshl_add_u64 v[158:159], v[148:149], 0, s[26:27]
	s_mov_b32 s26, 0
	v_mov_b32_e32 v0, v195
	v_mov_b32_e32 v1, v195
	v_mov_b32_e32 v2, v195
	v_mov_b32_e32 v3, v195
	v_mov_b32_e32 v4, v195
	v_mov_b32_e32 v5, v195
	v_mov_b32_e32 v6, v195
	v_mov_b32_e32 v7, v195
	v_mov_b32_e32 v8, v195
	v_mov_b32_e32 v9, v195
	v_mov_b32_e32 v10, v195
	v_mov_b32_e32 v11, v195
	v_mov_b32_e32 v12, v195
	v_mov_b32_e32 v13, v195
	v_mov_b32_e32 v14, v195
	v_mov_b32_e32 v15, v195
	v_mov_b32_e32 v16, v195
	v_mov_b32_e32 v17, v195
	v_mov_b32_e32 v18, v195
	v_mov_b32_e32 v19, v195
	v_mov_b32_e32 v20, v195
	v_mov_b32_e32 v21, v195
	v_mov_b32_e32 v22, v195
	v_mov_b32_e32 v23, v195
	v_mov_b32_e32 v24, v195
	v_mov_b32_e32 v25, v195
	v_mov_b32_e32 v26, v195
	v_mov_b32_e32 v27, v195
	v_mov_b32_e32 v28, v195
	v_mov_b32_e32 v29, v195
	v_mov_b32_e32 v30, v195
	v_mov_b32_e32 v31, v195
	v_mov_b32_e32 v32, v195
	v_mov_b32_e32 v33, v195
	v_mov_b32_e32 v34, v195
	v_mov_b32_e32 v35, v195
	v_mov_b32_e32 v36, v195
	v_mov_b32_e32 v37, v195
	v_mov_b32_e32 v38, v195
	v_mov_b32_e32 v39, v195
	v_mov_b32_e32 v40, v195
	v_mov_b32_e32 v41, v195
	v_mov_b32_e32 v42, v195
	v_mov_b32_e32 v43, v195
	v_mov_b32_e32 v44, v195
	v_mov_b32_e32 v45, v195
	v_mov_b32_e32 v46, v195
	v_mov_b32_e32 v47, v195
	s_mov_b64 s[48:49], -1
	s_mov_b32 s27, 0
	v_mov_b32_e32 v48, 0
	v_mov_b32_e32 v49, v155
	v_mov_b32_e32 v50, v155
	v_mov_b32_e32 v51, v155
	v_mov_b32_e32 v52, v155
	v_mov_b32_e32 v53, v155
	v_mov_b32_e32 v54, v155
	v_mov_b32_e32 v55, v155
	v_mov_b32_e32 v56, v155
	v_mov_b32_e32 v57, v155
	v_mov_b32_e32 v58, v155
	v_mov_b32_e32 v59, v155
	v_mov_b32_e32 v60, v155
	v_mov_b32_e32 v61, v155
	v_mov_b32_e32 v62, v155
	v_mov_b32_e32 v63, v155
	s_add_i32 s19, s27, 1
	s_cmp_ge_u32 s19, s69
	s_mov_b64 s[40:41], -1
	s_cbranch_scc0 .LBB0_239

; #define AT_WAITBAR(N) asm volatile("s_waitcnt vmcnt(%0) lgkmcnt(0)\n\ts_barrier" :: "n"(N) : "memory")
; template <int DQK, int DV, bool BAND>
; DI void attn_unit(const AttnArgs& a, LAS unsigned char* lds, int tid) {
;     ...
;             if (t + 1 < t_hi) AT_WAITBAR(NLD); else AT_WAITBAR(0);
;             vnext = vcur == 32768 ? 0 : vcur + 16384; const int vnn = vnext == 32768 ? 0 : vnext + 16384;
;             if (t + 2 < t_hi) AT_DMA(t + 2, vnn);
.LBB0_241:
	s_add_i32 s24, s26, 0x4000
	s_cmpk_lg_u32 s26, 0x8000
	s_cselect_b32 s24, s24, 0
	s_add_i32 s27, s27, 2
	s_cmp_ge_u32 s27, s69
	s_cbranch_scc1 .LBB0_243
	s_add_i32 s27, s24, 0x4000
	s_cmpk_lg_u32 s24, 0x8000
	s_cselect_b32 s27, s27, 0
	s_add_i32 s34, s17, s27
	s_mov_b32 m0, s34
	s_nop 0
	global_load_lds_dwordx4 v[158:159], off
	s_add_i32 s27, s18, s27
	s_mov_b32 m0, s27
	s_nop 0
	global_load_lds_dwordx4 v[156:157], off

; template <int DQK, int DV, bool BAND>
; DI void attn_unit(const AttnArgs& a, LAS unsigned char* lds, int tid) {
;     ...
;         for (int t = t_lo; t < t_hi; ++t) AT_DMA(t, (t - t_lo) * 8192);
.LBB0_270:
	v_lshl_add_u64 v[4:5], v[2:3], 0, s[46:47]
	s_mov_b32 m0, s41
	s_nop 0
	global_load_lds_dwordx4 v[4:5], off
	s_add_i32 s53, s41, 0xc000
	s_add_i32 s51, s51, 1
	s_addk_i32 s41, 0x2000
	v_lshl_add_u64 v[4:5], v[0:1], 0, s[46:47]
	s_mov_b32 m0, s53
	s_nop 0
	global_load_lds_dwordx4 v[4:5], off
	s_add_u32 s46, s46, s66
	s_addc_u32 s47, s47, 0
	s_cmp_lt_i32 s51, s35
	s_cbranch_scc1 .LBB0_270
	v_readlane_b32 s72, v255, 4
	v_readlane_b32 s70, v255, 6
	v_readlane_b32 s67, v253, 59
	v_readlane_b32 s66, v253, 60
	s_mov_b64 s[74:75], 0x60000
	s_mov_b64 s[76:77], 0x30000
	v_readlane_b32 s73, v255, 5
	v_readlane_b32 s71, v255, 7
